# v67 + residual-norm phases: the loop-top waits that only drained the previous rows' stores are dropped (explicit vmcnt(0) kept on the loop-entry and mod-reload paths)
# baseline (speedup 1.0000x reference)
.LBB0_460:
	v_mbcnt_lo_u32_b32 v25, -1, 0
	v_mbcnt_hi_u32_b32 v25, -1, v25
	v_and_b32_e32 v26, 64, v25
	v_add_u32_e32 v26, 64, v26
	v_xor_b32_e32 v27, 1, v25
	v_cmp_lt_i32_e32 vcc, v27, v26
	v_mov_b32_e32 v123, 0
	v_mov_b32_e32 v121, v123
	v_cndmask_b32_e32 v27, v25, v27, vcc
	v_lshlrev_b32_e32 v131, 2, v27
	v_xor_b32_e32 v27, 2, v25
	v_cmp_lt_i32_e32 vcc, v27, v26
	s_ashr_i32 s19, s18, 31
	s_mov_b64 s[20:21], 0x54000000
	v_cndmask_b32_e32 v27, v25, v27, vcc
	v_lshlrev_b32_e32 v140, 2, v27
	v_xor_b32_e32 v27, 4, v25
	v_cmp_lt_i32_e32 vcc, v27, v26
	v_lshl_add_u64 v[128:129], s[2:3], 0, v[120:121]
	v_lshl_add_u64 v[132:133], s[10:11], 0, v[122:123]
	v_cndmask_b32_e32 v27, v25, v27, vcc
	v_lshlrev_b32_e32 v141, 2, v27
	v_xor_b32_e32 v27, 8, v25
	v_cmp_lt_i32_e32 vcc, v27, v26
	s_add_i32 s10, s18, 3
	s_lshl_b64 s[2:3], s[18:19], 11
	v_cndmask_b32_e32 v27, v25, v27, vcc
	v_lshlrev_b32_e32 v142, 2, v27
	v_xor_b32_e32 v27, 16, v25
	v_cmp_lt_i32_e32 vcc, v27, v26
	v_lshlrev_b32_e32 v130, 1, v24
	v_lshl_add_u64 v[136:137], s[6:7], 0, v[122:123]
	v_cndmask_b32_e32 v27, v25, v27, vcc
	v_lshlrev_b32_e32 v143, 2, v27
	v_xor_b32_e32 v27, 32, v25
	v_cmp_lt_i32_e32 vcc, v27, v26
	s_mov_b32 s36, -1
	v_lshl_add_u64 v[134:135], s[16:17], 0, v[122:123]
	v_cndmask_b32_e32 v25, v25, v27, vcc
	v_lshl_add_u64 v[26:27], s[12:13], 0, v[120:121]
	v_lshl_add_u64 v[124:125], v[26:27], 0, s[20:21]
	v_lshl_add_u64 v[26:27], s[14:15], 0, v[120:121]
	s_add_u32 s14, s14, s2
	s_addc_u32 s15, s15, s3
	s_add_u32 s12, s12, s2
	s_addc_u32 s13, s13, s3
	s_add_u32 s8, s8, s2
	s_addc_u32 s9, s9, s3
	s_lshl_b64 s[2:3], s[18:19], 12
	s_add_u32 s2, s6, s2
	s_addc_u32 s3, s7, s3
	v_lshlrev_b32_e32 v144, 2, v25
	s_mov_b64 s[20:21], 0x9000000
	v_lshl_add_u64 v[24:25], s[2:3], 0, v[122:123]
	s_mov_b64 s[6:7], 0x2000
	v_lshl_add_u64 v[126:127], v[26:27], 0, s[20:21]
	v_lshl_add_u64 v[138:139], v[24:25], 0, s[6:7]
	s_mov_b64 s[16:17], 0x4000
	s_mov_b64 s[18:19], 0x3000
	s_movk_i32 s22, 0x4000
	s_movk_i32 s23, 0x3000
	v_mov_b32_e32 v145, 0x358637bd
	s_mov_b32 s25, 0xf800000
	v_mov_b32_e32 v146, 0x260
	s_brev_b32 s26, 42
	s_mov_b32 s27, 0x9000000
	s_waitcnt vmcnt(0)
	s_branch .LBB0_463

.LBB0_463:
	s_add_i32 s2, s10, -3
	s_ashr_i32 s2, s2, 13
	s_cmp_eq_u32 s2, s36
	s_cbranch_scc1 .LBB0_465
	s_mul_i32 s11, s2, 0x6000
	s_mul_hi_i32 s3, s2, 0x6000
	s_add_u32 s20, s48, s11
	s_addc_u32 s21, s49, s3
	v_lshlrev_b32_e32 v122, 4, v130
	v_lshl_add_u64 v[24:25], s[20:21], 0, v[122:123]
	v_add_co_u32_e32 v30, vcc, s22, v24
	v_lshl_add_u64 v[26:27], v[24:25], 0, s[6:7]
	s_nop 0
	v_addc_co_u32_e32 v31, vcc, 0, v25, vcc
	v_add_co_u32_e32 v40, vcc, s23, v24
	v_lshl_add_u64 v[28:29], v[24:25], 0, s[16:17]
	s_nop 0
	v_addc_co_u32_e32 v41, vcc, 0, v25, vcc
	v_lshl_add_u64 v[32:33], v[24:25], 0, s[18:19]
	global_load_dwordx4 v[36:39], v[132:133], off offset:16
	global_load_dwordx4 v[48:51], v[132:133], off
	global_load_dwordx4 v[44:47], v[30:31], off
	global_load_dwordx4 v[52:55], v[26:27], off offset:16
	global_load_dwordx4 v[56:59], v[28:29], off offset:16
	global_load_dwordx4 v[60:63], v[132:133], off offset:2064
	global_load_dwordx4 v[64:67], v[132:133], off offset:2048
	global_load_dwordx4 v[68:71], v[26:27], off offset:2048
	global_load_dwordx4 v[72:75], v[28:29], off offset:2064
	global_load_dwordx4 v[76:79], v[28:29], off offset:2048
	global_load_dwordx4 v[80:83], v[26:27], off offset:2064
	global_load_dwordx4 v[84:87], v[40:41], off offset:-4096
	global_load_dwordx4 v[88:91], v[134:135], off
	global_load_dwordx4 v[92:95], v[134:135], off offset:16
	global_load_dwordx4 v[148:151], v[134:135], off offset:2064
	global_load_dwordx4 v[152:155], v[134:135], off offset:2048
	global_load_dwordx4 v[24:27], v[32:33], off offset:2064
	global_load_dwordx4 v[28:31], v[32:33], off offset:16
	s_nop 0
	global_load_dwordx4 v[32:35], v[32:33], off offset:2048
	s_nop 0
	global_load_dwordx4 v[40:43], v[40:41], off
	s_mov_b32 s36, s2
	s_waitcnt vmcnt(17)
	v_pk_add_f32 v[156:157], v[46:47], 1.0 op_sel_hi:[1,0]
	v_pk_add_f32 v[158:159], v[44:45], 1.0 op_sel_hi:[1,0]
	s_waitcnt vmcnt(16)
	v_pk_mul_f32 v[38:39], v[38:39], v[54:55]
	v_pk_mul_f32 v[36:37], v[36:37], v[52:53]
	s_waitcnt vmcnt(15)
	v_pk_add_f32 v[52:53], v[58:59], 1.0 op_sel_hi:[1,0]
	v_pk_add_f32 v[54:55], v[56:57], 1.0 op_sel_hi:[1,0]
	s_waitcnt vmcnt(12)
	v_pk_mul_f32 v[46:47], v[66:67], v[70:71]
	v_pk_mul_f32 v[44:45], v[64:65], v[68:69]
	s_waitcnt vmcnt(10)
	v_pk_add_f32 v[56:57], v[78:79], 1.0 op_sel_hi:[1,0]
	v_pk_add_f32 v[58:59], v[76:77], 1.0 op_sel_hi:[1,0]
	v_pk_add_f32 v[64:65], v[74:75], 1.0 op_sel_hi:[1,0]
	v_pk_add_f32 v[66:67], v[72:73], 1.0 op_sel_hi:[1,0]
	s_waitcnt vmcnt(9)
	v_pk_mul_f32 v[62:63], v[62:63], v[82:83]
	v_pk_mul_f32 v[60:61], v[60:61], v[80:81]
	s_waitcnt vmcnt(8)
	v_pk_mul_f32 v[78:79], v[50:51], v[86:87]
	v_pk_mul_f32 v[76:77], v[48:49], v[84:85]
	s_waitcnt vmcnt(7)
	v_pk_mul_f32 v[82:83], v[90:91], v[156:157]
	v_pk_mul_f32 v[80:81], v[88:89], v[158:159]
	s_waitcnt vmcnt(6)
	v_pk_mul_f32 v[86:87], v[94:95], v[52:53]
	v_pk_mul_f32 v[84:85], v[92:93], v[54:55]
	s_waitcnt vmcnt(4)
	v_pk_mul_f32 v[90:91], v[154:155], v[56:57]
	v_pk_mul_f32 v[88:89], v[152:153], v[58:59]
	v_pk_mul_f32 v[94:95], v[150:151], v[64:65]
	v_pk_mul_f32 v[92:93], v[148:149], v[66:67]
	s_waitcnt vmcnt(0)
.LBB0_465:
	s_add_i32 s37, s10, -1
	v_mov_b64_e32 v[56:57], v[96:97]
	v_mov_b64_e32 v[64:65], v[104:105]
	v_mov_b64_e32 v[48:49], v[100:101]
	v_mov_b64_e32 v[52:53], v[108:109]
	v_mov_b64_e32 v[68:69], v[116:117]
	v_mov_b64_e32 v[72:73], v[112:113]
	s_cmp_ge_i32 s37, s24
	v_mov_b64_e32 v[58:59], v[98:99]
	v_mov_b64_e32 v[66:67], v[106:107]
	v_mov_b64_e32 v[50:51], v[102:103]
	v_mov_b64_e32 v[54:55], v[110:111]
	v_mov_b64_e32 v[70:71], v[118:119]
	v_mov_b64_e32 v[74:75], v[114:115]
	s_cbranch_scc1 .LBB0_467
	v_lshl_add_u64 v[68:69], s[8:9], 0, v[120:121]
	global_load_dwordx4 v[48:51], v[138:139], off offset:16
	global_load_dwordx4 v[52:55], v[138:139], off
	global_load_dwordx4 v[56:59], v[138:139], off offset:2064
	global_load_dwordx4 v[64:67], v[138:139], off offset:2048
	v_add_co_u32_e32 v72, vcc, 0xd101000, v68
	s_nop 1
	v_addc_co_u32_e32 v73, vcc, 0, v69, vcc
	global_load_dwordx4 v[68:71], v[72:73], off
	s_nop 0
	global_load_dwordx4 v[72:75], v[72:73], off offset:1024

.LBB0_679:
	v_mbcnt_lo_u32_b32 v17, -1, 0
	v_mbcnt_hi_u32_b32 v17, -1, v17
	v_and_b32_e32 v18, 64, v17
	v_add_u32_e32 v18, 64, v18
	v_xor_b32_e32 v19, 1, v17
	v_cmp_lt_i32_e32 vcc, v19, v18
	v_mov_b32_e32 v99, 0
	v_mov_b32_e32 v97, v99
	v_cndmask_b32_e32 v19, v17, v19, vcc
	v_lshlrev_b32_e32 v109, 2, v19
	v_xor_b32_e32 v19, 2, v17
	v_cmp_lt_i32_e32 vcc, v19, v18
	v_lshlrev_b32_e32 v98, 5, v16
	s_ashr_i32 s19, s18, 31
	v_cndmask_b32_e32 v19, v17, v19, vcc
	v_lshlrev_b32_e32 v114, 2, v19
	v_xor_b32_e32 v19, 4, v17
	v_cmp_lt_i32_e32 vcc, v19, v18
	s_mov_b64 s[22:23], 0x54000000
	v_lshl_add_u64 v[106:107], s[2:3], 0, v[96:97]
	v_cndmask_b32_e32 v19, v17, v19, vcc
	v_lshlrev_b32_e32 v115, 2, v19
	v_xor_b32_e32 v19, 8, v17
	v_cmp_lt_i32_e32 vcc, v19, v18
	v_lshl_add_u64 v[110:111], s[6:7], 0, v[98:99]
	s_add_i32 s6, s18, 3
	v_cndmask_b32_e32 v19, v17, v19, vcc
	v_lshlrev_b32_e32 v116, 2, v19
	v_xor_b32_e32 v19, 16, v17
	v_cmp_lt_i32_e32 vcc, v19, v18
	s_lshl_b64 s[2:3], s[18:19], 11
	s_mov_b32 s40, -1
	v_cndmask_b32_e32 v19, v17, v19, vcc
	v_lshlrev_b32_e32 v117, 2, v19
	v_xor_b32_e32 v19, 32, v17
	v_cmp_lt_i32_e32 vcc, v19, v18
	v_lshl_add_u64 v[104:105], s[20:21], 0, v[96:97]
	v_lshlrev_b32_e32 v108, 1, v16
	v_cndmask_b32_e32 v17, v17, v19, vcc
	v_lshl_add_u64 v[18:19], s[10:11], 0, v[96:97]
	v_lshl_add_u64 v[100:101], v[18:19], 0, s[22:23]
	v_lshl_add_u64 v[18:19], s[8:9], 0, v[96:97]
	s_add_u32 s8, s8, s2
	s_addc_u32 s9, s9, s3
	s_add_u32 s10, s10, s2
	s_addc_u32 s11, s11, s3
	s_add_u32 s12, s12, s2
	s_addc_u32 s13, s13, s3
	s_mov_b64 s[22:23], 0x9000000
	s_add_u32 s14, s14, s2
	v_lshlrev_b32_e32 v118, 2, v17
	v_lshl_add_u64 v[102:103], v[18:19], 0, s[22:23]
	v_lshl_add_u64 v[112:113], s[16:17], 0, v[98:99]
	s_addc_u32 s15, s15, s3
	s_mov_b64 s[16:17], 0x5000
	s_mov_b64 s[18:19], 0xd9000
	s_mov_b64 s[20:21], 0xd8000
	s_movk_i32 s24, 0x5000
	s_mov_b32 s25, 0xd9000
	s_mov_b32 s27, 0xd8000
	v_mov_b32_e32 v119, 0x358637bd
	s_mov_b32 s36, 0xf800000
	v_mov_b32_e32 v120, 0x260
	s_brev_b32 s37, 42
	s_mov_b32 s38, 0x9000000
	s_waitcnt vmcnt(0)
	s_branch .LBB0_682

.LBB0_682:
	s_add_i32 s2, s6, -3
	s_ashr_i32 s2, s2, 13
	s_cmp_eq_u32 s2, s40
	s_cbranch_scc1 .LBB0_684
	s_mul_i32 s7, s2, 0x6000
	s_mul_hi_i32 s3, s2, 0x6000
	s_add_u32 s22, s46, s7
	s_addc_u32 s23, s47, s3
	v_lshlrev_b32_e32 v98, 4, v108
	v_lshl_add_u64 v[16:17], s[22:23], 0, v[98:99]
	v_add_co_u32_e32 v26, vcc, s24, v16
	v_lshl_add_u64 v[18:19], v[16:17], 0, s[16:17]
	s_nop 0
	v_addc_co_u32_e32 v27, vcc, 0, v17, vcc
	v_lshl_add_u64 v[24:25], v[16:17], 0, s[18:19]
	global_load_dwordx4 v[20:23], v[110:111], off offset:16
	global_load_dwordx4 v[40:43], v[110:111], off
	global_load_dwordx4 v[44:47], v[26:27], off
	global_load_dwordx4 v[32:35], v[18:19], off offset:16
	global_load_dwordx4 v[48:51], v[24:25], off offset:16
	global_load_dwordx4 v[52:55], v[110:111], off offset:2064
	global_load_dwordx4 v[56:59], v[110:111], off offset:2048
	global_load_dwordx4 v[60:63], v[18:19], off offset:2048
	global_load_dwordx4 v[64:67], v[24:25], off offset:2064
	global_load_dwordx4 v[68:71], v[24:25], off offset:2048
	global_load_dwordx4 v[72:75], v[112:113], off offset:16
	global_load_dwordx4 v[76:79], v[112:113], off
	global_load_dwordx4 v[122:125], v[18:19], off offset:2064
	v_add_co_u32_e32 v18, vcc, s25, v16
	v_lshl_add_u64 v[28:29], v[16:17], 0, s[20:21]
	s_nop 0
	v_addc_co_u32_e32 v19, vcc, 0, v17, vcc
	v_add_co_u32_e32 v36, vcc, s27, v16
	global_load_dwordx4 v[126:129], v[18:19], off
	global_load_dwordx4 v[130:133], v[112:113], off offset:2064
	global_load_dwordx4 v[134:137], v[112:113], off offset:2048
	v_addc_co_u32_e32 v37, vcc, 0, v17, vcc
	global_load_dwordx4 v[16:19], v[28:29], off offset:2064
	global_load_dwordx4 v[24:27], v[28:29], off offset:16
	s_nop 0
	global_load_dwordx4 v[28:31], v[28:29], off offset:2048
	s_nop 0
	global_load_dwordx4 v[36:39], v[36:37], off
	s_mov_b32 s40, s2
	s_waitcnt vmcnt(15)
	v_pk_add_f32 v[50:51], v[50:51], 1.0 op_sel_hi:[1,0]
	v_pk_add_f32 v[48:49], v[48:49], 1.0 op_sel_hi:[1,0]
	s_waitcnt vmcnt(10)
	v_pk_add_f32 v[70:71], v[70:71], 1.0 op_sel_hi:[1,0]
	v_pk_mul_f32 v[22:23], v[22:23], v[34:35]
	v_pk_mul_f32 v[20:21], v[20:21], v[32:33]
	v_pk_mul_f32 v[34:35], v[58:59], v[62:63]
	v_pk_mul_f32 v[32:33], v[56:57], v[60:61]
	v_pk_add_f32 v[68:69], v[68:69], 1.0 op_sel_hi:[1,0]
	s_waitcnt vmcnt(7)
	v_pk_mul_f32 v[58:59], v[54:55], v[124:125]
	v_pk_mul_f32 v[56:57], v[52:53], v[122:123]
	v_pk_add_f32 v[52:53], v[66:67], 1.0 op_sel_hi:[1,0]
	v_pk_add_f32 v[54:55], v[64:65], 1.0 op_sel_hi:[1,0]
	v_pk_mul_f32 v[62:63], v[42:43], v[46:47]
	v_pk_mul_f32 v[60:61], v[40:41], v[44:45]
	s_waitcnt vmcnt(6)
	v_pk_add_f32 v[40:41], v[128:129], 1.0 op_sel_hi:[1,0]
	v_pk_add_f32 v[42:43], v[126:127], 1.0 op_sel_hi:[1,0]
	v_pk_mul_f32 v[66:67], v[74:75], v[50:51]
	v_pk_mul_f32 v[64:65], v[72:73], v[48:49]
	s_waitcnt vmcnt(4)
	v_pk_mul_f32 v[70:71], v[136:137], v[70:71]
	v_pk_mul_f32 v[68:69], v[134:135], v[68:69]
	v_pk_mul_f32 v[74:75], v[132:133], v[52:53]
	v_pk_mul_f32 v[72:73], v[130:131], v[54:55]
	v_pk_mul_f32 v[78:79], v[78:79], v[40:41]
	v_pk_mul_f32 v[76:77], v[76:77], v[42:43]
	s_waitcnt vmcnt(0)
.LBB0_684:
	s_add_i32 s39, s6, -1
	v_mov_b64_e32 v[44:45], v[92:93]
	v_mov_b64_e32 v[52:53], v[88:89]
	v_mov_b64_e32 v[40:41], v[84:85]
	v_mov_b64_e32 v[48:49], v[80:81]
	s_cmp_ge_i32 s39, s26
	v_mov_b64_e32 v[46:47], v[94:95]
	v_mov_b64_e32 v[54:55], v[90:91]
	v_mov_b64_e32 v[42:43], v[86:87]
	v_mov_b64_e32 v[50:51], v[82:83]
	s_cbranch_scc1 .LBB0_686
	v_lshl_add_u64 v[40:41], s[12:13], 0, v[96:97]
	v_add_co_u32_e32 v46, vcc, 0x54001000, v40
	v_lshl_add_u64 v[44:45], s[14:15], 0, v[96:97]
	s_nop 0
	v_addc_co_u32_e32 v47, vcc, 0, v41, vcc
	v_add_co_u32_e32 v122, vcc, 0xd101000, v44
	global_load_dwordx4 v[40:43], v[46:47], off
	global_load_dwordx4 v[48:51], v[46:47], off offset:1024
	v_addc_co_u32_e32 v123, vcc, 0, v45, vcc
	global_load_dwordx4 v[44:47], v[122:123], off
	global_load_dwordx4 v[52:55], v[122:123], off offset:1024

.LBB0_1184:
	v_mbcnt_hi_u32_b32 v17, -1, v252
	v_and_b32_e32 v18, 64, v17
	v_add_u32_e32 v18, 64, v18
	v_xor_b32_e32 v19, 1, v17
	v_cmp_lt_i32_e32 vcc, v19, v18
	v_mov_b32_e32 v99, 0
	v_mov_b32_e32 v97, v99
	v_cndmask_b32_e32 v19, v17, v19, vcc
	v_lshlrev_b32_e32 v109, 2, v19
	v_xor_b32_e32 v19, 2, v17
	v_cmp_lt_i32_e32 vcc, v19, v18
	v_lshlrev_b32_e32 v98, 5, v16
	s_ashr_i32 s19, s18, 31
	v_cndmask_b32_e32 v19, v17, v19, vcc
	v_lshlrev_b32_e32 v114, 2, v19
	v_xor_b32_e32 v19, 4, v17
	v_cmp_lt_i32_e32 vcc, v19, v18
	s_mov_b64 s[22:23], 0x54000000
	v_lshl_add_u64 v[106:107], s[2:3], 0, v[96:97]
	v_cndmask_b32_e32 v19, v17, v19, vcc
	v_lshlrev_b32_e32 v115, 2, v19
	v_xor_b32_e32 v19, 8, v17
	v_cmp_lt_i32_e32 vcc, v19, v18
	v_lshl_add_u64 v[110:111], s[6:7], 0, v[98:99]
	s_add_i32 s6, s18, 3
	v_cndmask_b32_e32 v19, v17, v19, vcc
	v_lshlrev_b32_e32 v116, 2, v19
	v_xor_b32_e32 v19, 16, v17
	v_cmp_lt_i32_e32 vcc, v19, v18
	s_lshl_b64 s[2:3], s[18:19], 11
	s_mov_b32 s39, -1
	v_cndmask_b32_e32 v19, v17, v19, vcc
	v_lshlrev_b32_e32 v117, 2, v19
	v_xor_b32_e32 v19, 32, v17
	v_cmp_lt_i32_e32 vcc, v19, v18
	v_lshl_add_u64 v[104:105], s[20:21], 0, v[96:97]
	v_lshlrev_b32_e32 v108, 1, v16
	v_cndmask_b32_e32 v17, v17, v19, vcc
	v_lshl_add_u64 v[18:19], s[10:11], 0, v[96:97]
	v_lshl_add_u64 v[100:101], v[18:19], 0, s[22:23]
	v_lshl_add_u64 v[18:19], s[8:9], 0, v[96:97]
	s_add_u32 s8, s8, s2
	s_addc_u32 s9, s9, s3
	s_add_u32 s10, s10, s2
	s_addc_u32 s11, s11, s3
	s_add_u32 s12, s12, s2
	s_addc_u32 s13, s13, s3
	s_mov_b64 s[22:23], 0x9000000
	s_add_u32 s14, s14, s2
	v_lshlrev_b32_e32 v118, 2, v17
	v_lshl_add_u64 v[102:103], v[18:19], 0, s[22:23]
	v_lshl_add_u64 v[112:113], s[16:17], 0, v[98:99]
	s_addc_u32 s15, s15, s3
	s_mov_b64 s[16:17], 0xda000
	s_mov_b64 s[18:19], 0xdc000
	s_mov_b64 s[20:21], 0xdb000
	s_mov_b32 s24, 0xdc000
	s_mov_b32 s25, 0xdb000
	v_mov_b32_e32 v119, 0x358637bd
	s_mov_b32 s27, 0xf800000
	v_mov_b32_e32 v120, 0x260
	s_brev_b32 s36, 42
	s_mov_b32 s37, 0x9000000
	s_waitcnt vmcnt(0)
	s_branch .LBB0_1187

.LBB0_1187:
	s_add_i32 s2, s6, -3
	s_ashr_i32 s2, s2, 13
	s_cmp_eq_u32 s2, s39
	s_cbranch_scc1 .LBB0_1189
	s_mul_i32 s7, s2, 0x6000
	s_mul_hi_i32 s3, s2, 0x6000
	s_add_u32 s22, s52, s7
	s_addc_u32 s23, s53, s3
	v_lshlrev_b32_e32 v98, 4, v108
	v_lshl_add_u64 v[16:17], s[22:23], 0, v[98:99]
	v_add_co_u32_e32 v22, vcc, s24, v16
	v_lshl_add_u64 v[18:19], v[16:17], 0, s[16:17]
	s_nop 0
	v_addc_co_u32_e32 v23, vcc, 0, v17, vcc
	v_add_co_u32_e32 v32, vcc, s25, v16
	v_lshl_add_u64 v[20:21], v[16:17], 0, s[18:19]
	s_nop 0
	v_addc_co_u32_e32 v33, vcc, 0, v17, vcc
	v_lshl_add_u64 v[24:25], v[16:17], 0, s[20:21]
	global_load_dwordx4 v[28:31], v[110:111], off offset:16
	global_load_dwordx4 v[40:43], v[110:111], off
	global_load_dwordx4 v[36:39], v[22:23], off
	global_load_dwordx4 v[44:47], v[18:19], off offset:16
	global_load_dwordx4 v[48:51], v[20:21], off offset:16
	global_load_dwordx4 v[52:55], v[110:111], off offset:2064
	global_load_dwordx4 v[56:59], v[110:111], off offset:2048
	global_load_dwordx4 v[60:63], v[18:19], off offset:2048
	global_load_dwordx4 v[64:67], v[20:21], off offset:2064
	global_load_dwordx4 v[68:71], v[20:21], off offset:2048
	global_load_dwordx4 v[72:75], v[18:19], off offset:2064
	global_load_dwordx4 v[76:79], v[32:33], off offset:-4096
	global_load_dwordx4 v[122:125], v[112:113], off
	global_load_dwordx4 v[126:129], v[112:113], off offset:16
	global_load_dwordx4 v[130:133], v[112:113], off offset:2064
	global_load_dwordx4 v[134:137], v[112:113], off offset:2048
	global_load_dwordx4 v[16:19], v[24:25], off offset:2064
	global_load_dwordx4 v[20:23], v[24:25], off offset:16
	s_nop 0
	global_load_dwordx4 v[24:27], v[24:25], off offset:2048
	s_nop 0
	global_load_dwordx4 v[32:35], v[32:33], off
	s_mov_b32 s39, s2
	s_waitcnt vmcnt(17)
	v_pk_add_f32 v[138:139], v[38:39], 1.0 op_sel_hi:[1,0]
	v_pk_add_f32 v[140:141], v[36:37], 1.0 op_sel_hi:[1,0]
	s_waitcnt vmcnt(16)
	v_pk_mul_f32 v[30:31], v[30:31], v[46:47]
	v_pk_mul_f32 v[28:29], v[28:29], v[44:45]
	s_waitcnt vmcnt(15)
	v_pk_add_f32 v[44:45], v[50:51], 1.0 op_sel_hi:[1,0]
	v_pk_add_f32 v[46:47], v[48:49], 1.0 op_sel_hi:[1,0]
	s_waitcnt vmcnt(12)
	v_pk_mul_f32 v[38:39], v[58:59], v[62:63]
	v_pk_mul_f32 v[36:37], v[56:57], v[60:61]
	s_waitcnt vmcnt(10)
	v_pk_add_f32 v[48:49], v[70:71], 1.0 op_sel_hi:[1,0]
	v_pk_add_f32 v[50:51], v[68:69], 1.0 op_sel_hi:[1,0]
	s_waitcnt vmcnt(9)
	v_pk_mul_f32 v[58:59], v[54:55], v[74:75]
	v_pk_mul_f32 v[56:57], v[52:53], v[72:73]
	v_pk_add_f32 v[52:53], v[66:67], 1.0 op_sel_hi:[1,0]
	v_pk_add_f32 v[54:55], v[64:65], 1.0 op_sel_hi:[1,0]
	s_waitcnt vmcnt(8)
	v_pk_mul_f32 v[62:63], v[42:43], v[78:79]
	v_pk_mul_f32 v[60:61], v[40:41], v[76:77]
	s_waitcnt vmcnt(7)
	v_pk_mul_f32 v[66:67], v[124:125], v[138:139]
	v_pk_mul_f32 v[64:65], v[122:123], v[140:141]
	s_waitcnt vmcnt(6)
	v_pk_mul_f32 v[70:71], v[128:129], v[44:45]
	v_pk_mul_f32 v[68:69], v[126:127], v[46:47]
	s_waitcnt vmcnt(4)
	v_pk_mul_f32 v[74:75], v[136:137], v[48:49]
	v_pk_mul_f32 v[72:73], v[134:135], v[50:51]
	v_pk_mul_f32 v[78:79], v[132:133], v[52:53]
	v_pk_mul_f32 v[76:77], v[130:131], v[54:55]
	s_waitcnt vmcnt(0)
.LBB0_1189:
	s_add_i32 s38, s6, -1
	v_mov_b64_e32 v[44:45], v[92:93]
	v_mov_b64_e32 v[52:53], v[88:89]
	v_mov_b64_e32 v[40:41], v[84:85]
	v_mov_b64_e32 v[48:49], v[80:81]
	s_cmp_ge_i32 s38, s26
	v_mov_b64_e32 v[46:47], v[94:95]
	v_mov_b64_e32 v[54:55], v[90:91]
	v_mov_b64_e32 v[42:43], v[86:87]
	v_mov_b64_e32 v[50:51], v[82:83]
	s_cbranch_scc1 .LBB0_1191
	v_lshl_add_u64 v[40:41], s[12:13], 0, v[96:97]
	v_add_co_u32_e32 v46, vcc, 0x54001000, v40
	v_lshl_add_u64 v[44:45], s[14:15], 0, v[96:97]
	s_nop 0
	v_addc_co_u32_e32 v47, vcc, 0, v41, vcc
	v_add_co_u32_e32 v122, vcc, 0xd101000, v44
	global_load_dwordx4 v[40:43], v[46:47], off
	global_load_dwordx4 v[48:51], v[46:47], off offset:1024
	v_addc_co_u32_e32 v123, vcc, 0, v45, vcc
	global_load_dwordx4 v[44:47], v[122:123], off
	global_load_dwordx4 v[52:55], v[122:123], off offset:1024

.LBB0_1403:
	v_mbcnt_hi_u32_b32 v17, -1, v252
	v_and_b32_e32 v18, 64, v17
	v_add_u32_e32 v18, 64, v18
	v_xor_b32_e32 v19, 1, v17
	v_cmp_lt_i32_e32 vcc, v19, v18
	v_mov_b32_e32 v99, 0
	v_mov_b32_e32 v97, v99
	v_cndmask_b32_e32 v19, v17, v19, vcc
	v_lshlrev_b32_e32 v109, 2, v19
	v_xor_b32_e32 v19, 2, v17
	v_cmp_lt_i32_e32 vcc, v19, v18
	v_lshlrev_b32_e32 v98, 5, v16
	s_ashr_i32 s19, s18, 31
	v_cndmask_b32_e32 v19, v17, v19, vcc
	v_lshlrev_b32_e32 v114, 2, v19
	v_xor_b32_e32 v19, 4, v17
	v_cmp_lt_i32_e32 vcc, v19, v18
	s_mov_b64 s[22:23], 0x54000000
	v_lshl_add_u64 v[106:107], s[2:3], 0, v[96:97]
	v_cndmask_b32_e32 v19, v17, v19, vcc
	v_lshlrev_b32_e32 v115, 2, v19
	v_xor_b32_e32 v19, 8, v17
	v_cmp_lt_i32_e32 vcc, v19, v18
	v_lshl_add_u64 v[110:111], s[6:7], 0, v[98:99]
	s_add_i32 s6, s18, 3
	v_cndmask_b32_e32 v19, v17, v19, vcc
	v_lshlrev_b32_e32 v116, 2, v19
	v_xor_b32_e32 v19, 16, v17
	v_cmp_lt_i32_e32 vcc, v19, v18
	s_lshl_b64 s[2:3], s[18:19], 11
	s_mov_b32 s40, -1
	v_cndmask_b32_e32 v19, v17, v19, vcc
	v_lshlrev_b32_e32 v117, 2, v19
	v_xor_b32_e32 v19, 32, v17
	v_cmp_lt_i32_e32 vcc, v19, v18
	v_lshl_add_u64 v[104:105], s[20:21], 0, v[96:97]
	v_lshlrev_b32_e32 v108, 1, v16
	v_cndmask_b32_e32 v17, v17, v19, vcc
	v_lshl_add_u64 v[18:19], s[10:11], 0, v[96:97]
	v_lshl_add_u64 v[100:101], v[18:19], 0, s[22:23]
	v_lshl_add_u64 v[18:19], s[8:9], 0, v[96:97]
	s_add_u32 s8, s8, s2
	s_addc_u32 s9, s9, s3
	s_add_u32 s10, s10, s2
	s_addc_u32 s11, s11, s3
	s_add_u32 s12, s12, s2
	s_addc_u32 s13, s13, s3
	s_mov_b64 s[22:23], 0x9000000
	s_add_u32 s14, s14, s2
	v_lshlrev_b32_e32 v118, 2, v17
	v_lshl_add_u64 v[102:103], v[18:19], 0, s[22:23]
	v_lshl_add_u64 v[112:113], s[16:17], 0, v[98:99]
	s_addc_u32 s15, s15, s3
	s_mov_b64 s[16:17], 0xdd000
	s_mov_b64 s[18:19], 0x1b1000
	s_mov_b64 s[20:21], 0x1b0000
	s_mov_b32 s24, 0xdd000
	s_mov_b32 s25, 0x1b1000
	s_mov_b32 s27, 0x1b0000
	v_mov_b32_e32 v119, 0x358637bd
	s_mov_b32 s36, 0xf800000
	v_mov_b32_e32 v120, 0x260
	s_brev_b32 s37, 42
	s_mov_b32 s38, 0x9000000
	s_waitcnt vmcnt(0)
	s_branch .LBB0_1406

.LBB0_2017:
	v_mbcnt_hi_u32_b32 v17, -1, v252
	v_and_b32_e32 v18, 64, v17
	v_add_u32_e32 v18, 64, v18
	v_xor_b32_e32 v19, 1, v17
	v_cmp_lt_i32_e32 vcc, v19, v18
	v_mov_b32_e32 v99, 0
	v_mov_b32_e32 v97, v99
	v_cndmask_b32_e32 v19, v17, v19, vcc
	v_lshlrev_b32_e32 v109, 2, v19
	v_xor_b32_e32 v19, 2, v17
	v_cmp_lt_i32_e32 vcc, v19, v18
	v_lshlrev_b32_e32 v98, 5, v16
	s_ashr_i32 s19, s18, 31
	v_cndmask_b32_e32 v19, v17, v19, vcc
	v_lshlrev_b32_e32 v114, 2, v19
	v_xor_b32_e32 v19, 4, v17
	v_cmp_lt_i32_e32 vcc, v19, v18
	s_mov_b64 s[22:23], 0x54000000
	v_lshl_add_u64 v[106:107], s[2:3], 0, v[96:97]
	v_cndmask_b32_e32 v19, v17, v19, vcc
	v_lshlrev_b32_e32 v115, 2, v19
	v_xor_b32_e32 v19, 8, v17
	v_cmp_lt_i32_e32 vcc, v19, v18
	v_lshl_add_u64 v[110:111], s[6:7], 0, v[98:99]
	s_add_i32 s6, s18, 3
	v_cndmask_b32_e32 v19, v17, v19, vcc
	v_lshlrev_b32_e32 v116, 2, v19
	v_xor_b32_e32 v19, 16, v17
	v_cmp_lt_i32_e32 vcc, v19, v18
	s_lshl_b64 s[2:3], s[18:19], 11
	s_mov_b32 s39, -1
	v_cndmask_b32_e32 v19, v17, v19, vcc
	v_lshlrev_b32_e32 v117, 2, v19
	v_xor_b32_e32 v19, 32, v17
	v_cmp_lt_i32_e32 vcc, v19, v18
	v_lshl_add_u64 v[104:105], s[20:21], 0, v[96:97]
	v_lshlrev_b32_e32 v108, 1, v16
	v_cndmask_b32_e32 v17, v17, v19, vcc
	v_lshl_add_u64 v[18:19], s[10:11], 0, v[96:97]
	v_lshl_add_u64 v[100:101], v[18:19], 0, s[22:23]
	v_lshl_add_u64 v[18:19], s[8:9], 0, v[96:97]
	s_add_u32 s8, s8, s2
	s_addc_u32 s9, s9, s3
	s_add_u32 s10, s10, s2
	s_addc_u32 s11, s11, s3
	s_add_u32 s12, s12, s2
	s_addc_u32 s13, s13, s3
	s_mov_b64 s[22:23], 0x9000000
	s_add_u32 s14, s14, s2
	v_lshlrev_b32_e32 v118, 2, v17
	v_lshl_add_u64 v[102:103], v[18:19], 0, s[22:23]
	v_lshl_add_u64 v[112:113], s[16:17], 0, v[98:99]
	s_addc_u32 s15, s15, s3
	s_mov_b64 s[16:17], 0x1b2000
	s_mov_b64 s[18:19], 0x1b4000
	s_mov_b64 s[20:21], 0x1b3000
	s_mov_b32 s24, 0x1b4000
	s_mov_b32 s25, 0x1b3000
	v_mov_b32_e32 v119, 0x358637bd
	s_mov_b32 s27, 0xf800000
	v_mov_b32_e32 v120, 0x260
	s_brev_b32 s36, 42
	s_mov_b32 s37, 0x9000000
	s_waitcnt vmcnt(0)
	s_branch .LBB0_2020

.LBB0_2020:
	s_add_i32 s2, s6, -3
	s_ashr_i32 s2, s2, 13
	s_cmp_eq_u32 s2, s39
	s_cbranch_scc1 .LBB0_2022
	s_mul_i32 s7, s2, 0x6000
	s_mul_hi_i32 s3, s2, 0x6000
	s_add_u32 s22, s46, s7
	s_addc_u32 s23, s47, s3
	v_lshlrev_b32_e32 v98, 4, v108
	v_lshl_add_u64 v[16:17], s[22:23], 0, v[98:99]
	v_add_co_u32_e32 v22, vcc, s24, v16
	v_lshl_add_u64 v[18:19], v[16:17], 0, s[16:17]
	s_nop 0
	v_addc_co_u32_e32 v23, vcc, 0, v17, vcc
	v_add_co_u32_e32 v32, vcc, s25, v16
	v_lshl_add_u64 v[20:21], v[16:17], 0, s[18:19]
	s_nop 0
	v_addc_co_u32_e32 v33, vcc, 0, v17, vcc
	v_lshl_add_u64 v[24:25], v[16:17], 0, s[20:21]
	global_load_dwordx4 v[28:31], v[110:111], off offset:16
	global_load_dwordx4 v[40:43], v[110:111], off
	global_load_dwordx4 v[36:39], v[22:23], off
	global_load_dwordx4 v[44:47], v[18:19], off offset:16
	global_load_dwordx4 v[48:51], v[20:21], off offset:16
	global_load_dwordx4 v[52:55], v[110:111], off offset:2064
	global_load_dwordx4 v[56:59], v[110:111], off offset:2048
	global_load_dwordx4 v[60:63], v[18:19], off offset:2048
	global_load_dwordx4 v[64:67], v[20:21], off offset:2064
	global_load_dwordx4 v[68:71], v[20:21], off offset:2048
	global_load_dwordx4 v[72:75], v[18:19], off offset:2064
	global_load_dwordx4 v[76:79], v[32:33], off offset:-4096
	global_load_dwordx4 v[122:125], v[112:113], off
	global_load_dwordx4 v[126:129], v[112:113], off offset:16
	global_load_dwordx4 v[130:133], v[112:113], off offset:2064
	global_load_dwordx4 v[134:137], v[112:113], off offset:2048
	global_load_dwordx4 v[16:19], v[24:25], off offset:2064
	global_load_dwordx4 v[20:23], v[24:25], off offset:16
	s_nop 0
	global_load_dwordx4 v[24:27], v[24:25], off offset:2048
	s_nop 0
	global_load_dwordx4 v[32:35], v[32:33], off
	s_mov_b32 s39, s2
	s_waitcnt vmcnt(17)
	v_pk_add_f32 v[138:139], v[38:39], 1.0 op_sel_hi:[1,0]
	v_pk_add_f32 v[140:141], v[36:37], 1.0 op_sel_hi:[1,0]
	s_waitcnt vmcnt(16)
	v_pk_mul_f32 v[30:31], v[30:31], v[46:47]
	v_pk_mul_f32 v[28:29], v[28:29], v[44:45]
	s_waitcnt vmcnt(15)
	v_pk_add_f32 v[44:45], v[50:51], 1.0 op_sel_hi:[1,0]
	v_pk_add_f32 v[46:47], v[48:49], 1.0 op_sel_hi:[1,0]
	s_waitcnt vmcnt(12)
	v_pk_mul_f32 v[38:39], v[58:59], v[62:63]
	v_pk_mul_f32 v[36:37], v[56:57], v[60:61]
	s_waitcnt vmcnt(10)
	v_pk_add_f32 v[48:49], v[70:71], 1.0 op_sel_hi:[1,0]
	v_pk_add_f32 v[50:51], v[68:69], 1.0 op_sel_hi:[1,0]
	s_waitcnt vmcnt(9)
	v_pk_mul_f32 v[58:59], v[54:55], v[74:75]
	v_pk_mul_f32 v[56:57], v[52:53], v[72:73]
	v_pk_add_f32 v[52:53], v[66:67], 1.0 op_sel_hi:[1,0]
	v_pk_add_f32 v[54:55], v[64:65], 1.0 op_sel_hi:[1,0]
	s_waitcnt vmcnt(8)
	v_pk_mul_f32 v[62:63], v[42:43], v[78:79]
	v_pk_mul_f32 v[60:61], v[40:41], v[76:77]
	s_waitcnt vmcnt(7)
	v_pk_mul_f32 v[66:67], v[124:125], v[138:139]
	v_pk_mul_f32 v[64:65], v[122:123], v[140:141]
	s_waitcnt vmcnt(6)
	v_pk_mul_f32 v[70:71], v[128:129], v[44:45]
	v_pk_mul_f32 v[68:69], v[126:127], v[46:47]
	s_waitcnt vmcnt(4)
	v_pk_mul_f32 v[74:75], v[136:137], v[48:49]
	v_pk_mul_f32 v[72:73], v[134:135], v[50:51]
	v_pk_mul_f32 v[78:79], v[132:133], v[52:53]
	v_pk_mul_f32 v[76:77], v[130:131], v[54:55]
	s_waitcnt vmcnt(0)

.LBB0_2236:
	v_mbcnt_hi_u32_b32 v17, -1, v252
	v_and_b32_e32 v18, 64, v17
	v_add_u32_e32 v18, 64, v18
	v_xor_b32_e32 v19, 1, v17
	v_cmp_lt_i32_e32 vcc, v19, v18
	v_mov_b32_e32 v99, 0
	v_mov_b32_e32 v97, v99
	v_cndmask_b32_e32 v19, v17, v19, vcc
	v_lshlrev_b32_e32 v109, 2, v19
	v_xor_b32_e32 v19, 2, v17
	v_cmp_lt_i32_e32 vcc, v19, v18
	v_lshlrev_b32_e32 v98, 5, v16
	s_ashr_i32 s19, s18, 31
	v_cndmask_b32_e32 v19, v17, v19, vcc
	v_lshlrev_b32_e32 v114, 2, v19
	v_xor_b32_e32 v19, 4, v17
	v_cmp_lt_i32_e32 vcc, v19, v18
	s_mov_b64 s[22:23], 0x54000000
	v_lshl_add_u64 v[106:107], s[2:3], 0, v[96:97]
	v_cndmask_b32_e32 v19, v17, v19, vcc
	v_lshlrev_b32_e32 v115, 2, v19
	v_xor_b32_e32 v19, 8, v17
	v_cmp_lt_i32_e32 vcc, v19, v18
	v_lshl_add_u64 v[110:111], s[6:7], 0, v[98:99]
	s_add_i32 s6, s18, 3
	v_cndmask_b32_e32 v19, v17, v19, vcc
	v_lshlrev_b32_e32 v116, 2, v19
	v_xor_b32_e32 v19, 16, v17
	v_cmp_lt_i32_e32 vcc, v19, v18
	s_lshl_b64 s[2:3], s[18:19], 11
	s_mov_b32 s40, -1
	v_cndmask_b32_e32 v19, v17, v19, vcc
	v_lshlrev_b32_e32 v117, 2, v19
	v_xor_b32_e32 v19, 32, v17
	v_cmp_lt_i32_e32 vcc, v19, v18
	v_lshl_add_u64 v[104:105], s[20:21], 0, v[96:97]
	v_lshlrev_b32_e32 v108, 1, v16
	v_cndmask_b32_e32 v17, v17, v19, vcc
	v_lshl_add_u64 v[18:19], s[10:11], 0, v[96:97]
	v_lshl_add_u64 v[100:101], v[18:19], 0, s[22:23]
	v_lshl_add_u64 v[18:19], s[8:9], 0, v[96:97]
	s_add_u32 s8, s8, s2
	s_addc_u32 s9, s9, s3
	s_add_u32 s10, s10, s2
	s_addc_u32 s11, s11, s3
	s_add_u32 s12, s12, s2
	s_addc_u32 s13, s13, s3
	s_mov_b64 s[22:23], 0x9000000
	s_add_u32 s14, s14, s2
	v_lshlrev_b32_e32 v118, 2, v17
	v_lshl_add_u64 v[102:103], v[18:19], 0, s[22:23]
	v_lshl_add_u64 v[112:113], s[16:17], 0, v[98:99]
	s_addc_u32 s15, s15, s3
	s_mov_b64 s[16:17], 0x1b5000
	s_mov_b64 s[18:19], 0x289000
	s_mov_b64 s[20:21], 0x288000
	s_mov_b32 s24, 0x1b5000
	s_mov_b32 s25, 0x289000
	s_mov_b32 s27, 0x288000
	v_mov_b32_e32 v119, 0x358637bd
	s_mov_b32 s36, 0xf800000
	v_mov_b32_e32 v120, 0x260
	s_brev_b32 s37, 42
	s_mov_b32 s38, 0x9000000
	s_waitcnt vmcnt(0)
	s_branch .LBB0_2239

.LBB0_2666:
	v_mbcnt_hi_u32_b32 v17, -1, v252
	v_and_b32_e32 v18, 64, v17
	v_add_u32_e32 v18, 64, v18
	v_xor_b32_e32 v19, 1, v17
	v_cmp_lt_i32_e32 vcc, v19, v18
	v_mov_b32_e32 v99, 0
	v_mov_b32_e32 v97, v99
	v_cndmask_b32_e32 v19, v17, v19, vcc
	v_lshlrev_b32_e32 v109, 2, v19
	v_xor_b32_e32 v19, 2, v17
	v_cmp_lt_i32_e32 vcc, v19, v18
	v_lshlrev_b32_e32 v98, 5, v16
	s_ashr_i32 s19, s18, 31
	v_cndmask_b32_e32 v19, v17, v19, vcc
	v_lshlrev_b32_e32 v114, 2, v19
	v_xor_b32_e32 v19, 4, v17
	v_cmp_lt_i32_e32 vcc, v19, v18
	s_mov_b64 s[22:23], 0x54000000
	v_lshl_add_u64 v[106:107], s[2:3], 0, v[96:97]
	v_cndmask_b32_e32 v19, v17, v19, vcc
	v_lshlrev_b32_e32 v115, 2, v19
	v_xor_b32_e32 v19, 8, v17
	v_cmp_lt_i32_e32 vcc, v19, v18
	v_lshl_add_u64 v[110:111], s[6:7], 0, v[98:99]
	s_add_i32 s6, s18, 3
	v_cndmask_b32_e32 v19, v17, v19, vcc
	v_lshlrev_b32_e32 v116, 2, v19
	v_xor_b32_e32 v19, 16, v17
	v_cmp_lt_i32_e32 vcc, v19, v18
	s_lshl_b64 s[2:3], s[18:19], 11
	s_mov_b32 s39, -1
	v_cndmask_b32_e32 v19, v17, v19, vcc
	v_lshlrev_b32_e32 v117, 2, v19
	v_xor_b32_e32 v19, 32, v17
	v_cmp_lt_i32_e32 vcc, v19, v18
	v_lshl_add_u64 v[104:105], s[20:21], 0, v[96:97]
	v_lshlrev_b32_e32 v108, 1, v16
	v_cndmask_b32_e32 v17, v17, v19, vcc
	v_lshl_add_u64 v[18:19], s[10:11], 0, v[96:97]
	v_lshl_add_u64 v[100:101], v[18:19], 0, s[22:23]
	v_lshl_add_u64 v[18:19], s[8:9], 0, v[96:97]
	s_add_u32 s8, s8, s2
	s_addc_u32 s9, s9, s3
	s_add_u32 s10, s10, s2
	s_addc_u32 s11, s11, s3
	s_add_u32 s12, s12, s2
	s_addc_u32 s13, s13, s3
	s_mov_b64 s[22:23], 0x9000000
	s_add_u32 s14, s14, s2
	v_lshlrev_b32_e32 v118, 2, v17
	v_lshl_add_u64 v[102:103], v[18:19], 0, s[22:23]
	v_lshl_add_u64 v[112:113], s[16:17], 0, v[98:99]
	s_addc_u32 s15, s15, s3
	s_mov_b64 s[16:17], 0x28a000
	s_mov_b64 s[18:19], 0x28c000
	s_mov_b64 s[20:21], 0x28b000
	s_mov_b32 s24, 0x28c000
	s_mov_b32 s25, 0x28b000
	v_mov_b32_e32 v119, 0x358637bd
	s_mov_b32 s27, 0xf800000
	v_mov_b32_e32 v120, 0x260
	s_brev_b32 s36, 42
	s_mov_b32 s37, 0x9000000
	s_waitcnt vmcnt(0)
	s_branch .LBB0_2669

.LBB0_2885:
	v_mbcnt_hi_u32_b32 v17, -1, v252
	v_and_b32_e32 v18, 64, v17
	v_add_u32_e32 v18, 64, v18
	v_xor_b32_e32 v19, 1, v17
	v_cmp_lt_i32_e32 vcc, v19, v18
	v_mov_b32_e32 v69, 0
	v_lshlrev_b32_e32 v68, 5, v16
	v_cndmask_b32_e32 v19, v17, v19, vcc
	v_lshlrev_b32_e32 v67, 2, v19
	v_xor_b32_e32 v19, 2, v17
	v_cmp_lt_i32_e32 vcc, v19, v18
	v_mov_b32_e32 v65, v69
	s_ashr_i32 s13, s12, 31
	v_cndmask_b32_e32 v19, v17, v19, vcc
	v_lshlrev_b32_e32 v80, 2, v19
	v_xor_b32_e32 v19, 4, v17
	v_cmp_lt_i32_e32 vcc, v19, v18
	v_lshl_add_u64 v[72:73], s[10:11], 0, v[68:69]
	v_lshl_add_u64 v[76:77], s[0:1], 0, v[64:65]
	v_cndmask_b32_e32 v19, v17, v19, vcc
	v_lshlrev_b32_e32 v81, 2, v19
	v_xor_b32_e32 v19, 8, v17
	v_cmp_lt_i32_e32 vcc, v19, v18
	s_add_i32 s10, s12, 3
	s_lshl_b64 s[0:1], s[12:13], 12
	v_cndmask_b32_e32 v19, v17, v19, vcc
	v_lshlrev_b32_e32 v82, 2, v19
	v_xor_b32_e32 v19, 16, v17
	s_add_u32 s0, s8, s0
	v_cmp_lt_i32_e32 vcc, v19, v18
	s_addc_u32 s1, s9, s1
	v_lshl_add_u64 v[78:79], s[0:1], 0, v[68:69]
	v_cndmask_b32_e32 v19, v17, v19, vcc
	s_lshl_b64 s[0:1], s[12:13], 11
	v_lshlrev_b32_e32 v83, 2, v19
	v_xor_b32_e32 v19, 32, v17
	s_add_u32 s4, s4, s0
	v_cmp_lt_i32_e32 vcc, v19, v18
	s_addc_u32 s5, s5, s1
	s_add_u32 s6, s6, s0
	v_cndmask_b32_e32 v17, v17, v19, vcc
	s_mov_b32 s18, -1
	v_lshlrev_b32_e32 v84, 2, v17
	v_lshlrev_b32_e32 v66, 1, v16
	v_lshl_add_u64 v[70:71], s[8:9], 0, v[68:69]
	v_lshl_add_u64 v[74:75], s[14:15], 0, v[64:65]
	s_addc_u32 s7, s7, s1
	s_mov_b64 s[8:9], 0x28d000
	s_mov_b32 s16, 0x28d000
	v_mov_b32_e32 v85, 0x358637bd
	s_mov_b32 s17, 0xf800000
	v_mov_b32_e32 v86, 0x260
	s_mov_b64 s[12:13], 0x2000
	s_waitcnt vmcnt(0)
	s_branch .LBB0_2888

.LBB0_2888:
	s_add_i32 s0, s10, -3
	s_ashr_i32 s0, s0, 13
	s_cmp_eq_u32 s0, s18
	s_cbranch_scc1 .LBB0_2890
	s_mul_i32 s11, s0, 0x6000
	s_mul_hi_i32 s1, s0, 0x6000
	s_add_u32 s14, s50, s11
	s_addc_u32 s15, s51, s1
	v_lshlrev_b32_e32 v68, 4, v66
	v_lshl_add_u64 v[36:37], s[14:15], 0, v[68:69]
	v_add_co_u32_e32 v90, vcc, s16, v36
	v_lshl_add_u64 v[88:89], v[36:37], 0, s[8:9]
	s_nop 0
	v_addc_co_u32_e32 v91, vcc, 0, v37, vcc
	global_load_dwordx4 v[16:19], v[72:73], off offset:16
	global_load_dwordx4 v[24:27], v[72:73], off
	global_load_dwordx4 v[20:23], v[72:73], off offset:2048
	global_load_dwordx4 v[28:31], v[88:89], off offset:16
	global_load_dwordx4 v[32:35], v[88:89], off offset:2048
	global_load_dwordx4 v[36:39], v[90:91], off
	global_load_dwordx4 v[40:43], v[72:73], off offset:2064
	global_load_dwordx4 v[44:47], v[88:89], off offset:2064
	s_mov_b32 s18, s0
	s_waitcnt vmcnt(4)
	v_pk_mul_f32 v[18:19], v[18:19], v[30:31]
	v_pk_mul_f32 v[16:17], v[16:17], v[28:29]
	s_waitcnt vmcnt(3)
	v_pk_mul_f32 v[22:23], v[22:23], v[34:35]
	v_pk_mul_f32 v[20:21], v[20:21], v[32:33]
	s_waitcnt vmcnt(2)
	v_pk_mul_f32 v[26:27], v[26:27], v[38:39]
	v_pk_mul_f32 v[24:25], v[24:25], v[36:37]
	s_waitcnt vmcnt(0)
	v_pk_mul_f32 v[30:31], v[42:43], v[46:47]
	v_pk_mul_f32 v[28:29], v[40:41], v[44:45]
	s_waitcnt vmcnt(0)
.LBB0_2890:
	s_add_i32 s19, s10, -1
	v_mov_b64_e32 v[36:37], v[60:61]
	v_mov_b64_e32 v[44:45], v[56:57]
	v_mov_b64_e32 v[32:33], v[52:53]
	v_mov_b64_e32 v[40:41], v[48:49]
	s_cmp_ge_i32 s19, s20
	v_mov_b64_e32 v[38:39], v[62:63]
	v_mov_b64_e32 v[46:47], v[58:59]
	v_mov_b64_e32 v[34:35], v[54:55]
	v_mov_b64_e32 v[42:43], v[50:51]
	s_cbranch_scc1 .LBB0_2892
	v_lshl_add_u64 v[32:33], s[4:5], 0, v[64:65]
	v_add_co_u32_e32 v38, vcc, 0x54001000, v32
	v_lshl_add_u64 v[36:37], s[6:7], 0, v[64:65]
	s_nop 0
	v_addc_co_u32_e32 v39, vcc, 0, v33, vcc
	v_add_co_u32_e32 v88, vcc, 0xd101000, v36
	global_load_dwordx4 v[32:35], v[38:39], off
	global_load_dwordx4 v[40:43], v[38:39], off offset:1024
	v_addc_co_u32_e32 v89, vcc, 0, v37, vcc
	global_load_dwordx4 v[36:39], v[88:89], off
	global_load_dwordx4 v[44:47], v[88:89], off offset:1024
